# EVENA chunk-state stores: 32 short stores per lane paired into 16 dword stores via DPP lane exchange + v_perm
# speedup vs baseline: 1.0053x; 1.0017x over previous
.LBB0_462:
	s_cmpk_gt_i32 s4, 0x3ff
	s_cbranch_scc1 .LBB0_465
	v_ashrrev_i32_e32 v38, 3, v53
	v_and_b32_e32 v0, 56, v72
	v_sub_u32_e32 v2, 63, v38
	v_lshlrev_b32_e32 v168, 3, v0
	v_cvt_f32_i32_e32 v39, v2
	v_lshl_add_u64 v[2:3], s[10:11], 0, v[168:169]
	s_mov_b64 s[12:13], 0x100000
	s_ashr_i32 s5, s5, 6
	v_lshl_add_u64 v[32:33], v[2:3], 0, s[12:13]
	s_movk_i32 s12, 0x110
	v_mul_lo_u32 v2, v38, s12
	s_lshl_b32 s12, s5, 5
	v_lshlrev_b32_e32 v3, 1, v0
	s_and_b32 s13, s12, 0x60
	v_add3_u32 v40, 0, v2, v3
	s_lshl_b32 s5, s5, 4
	s_lshl_b32 s12, s13, 1
	v_lshlrev_b32_e32 v2, 1, v53
	s_and_b32 s14, s5, 0xffffffc0
	s_add_i32 s12, s12, 0
	v_and_b32_e32 v4, 62, v2
	v_add_u32_e32 v5, s12, v4
	s_lshl_b32 s12, s14, 1
	s_add_i32 s12, s12, 0
	v_bfi_b32 v2, 63, v53, s5
	s_ashr_i32 s15, s14, 31
	s_ashr_i32 s5, s4, 31
	v_bfe_u32 v1, v53, 5, 1
	v_add_u32_e32 v6, s12, v4
	s_lshl_b32 s12, s4, 4
	s_lshl_b64 s[16:17], s[4:5], 15
	s_lshl_b64 s[14:15], s[14:15], 1
	v_mul_u32_u24_e32 v8, 0x880, v1
	s_add_u32 s14, s16, s14
	v_lshlrev_b32_e32 v1, 10, v1
	v_lshl_or_b32 v2, v2, 1, 64
	s_addc_u32 s15, s17, s15
	v_lshl_or_b32 v168, s13, 8, v1
	v_add_u32_e32 v7, 0, v2
	v_lshl_add_u64 v[2:3], s[14:15], 0, v[168:169]
	v_or_b32_e32 v2, v2, v4
	v_lshl_add_u64 v[2:3], s[10:11], 0, v[2:3]
	s_mov_b64 s[10:11], 0x11701b40
	v_lshl_add_u64 v[34:35], v[2:3], 0, s[10:11]
	v_lshlrev_b32_e32 v168, 1, v0
	v_add_u32_e32 v41, v5, v8
	v_add_u32_e32 v42, v6, v8
	v_add_u32_e32 v43, v7, v8
	v_and_b32_e32 v158, 1, v53
	v_mul_u32_u24_e32 v156, 0xfe, v158
	v_mov_b32_e32 v157, 0
	v_mov_b32_e32 v162, 0x5040100
	v_mov_b32_e32 v163, 0x3020706
	v_cmp_ne_u32_e32 vcc, 0, v158
	s_nop 1
	v_cndmask_b32_e32 v162, v162, v163, vcc
	s_and_b32 s13, s12, 0xfc0
	s_and_b32 s14, s12, 0xffffffc0
	s_and_b32 s26, s4, 3
	s_lshl_b32 s26, s26, 8
	v_mov_b64_e32 v[110:111], s[6:7]
	v_add_u32_e32 v113, s14, v38
	v_add_u32_e32 v112, s13, v38
	v_mad_i64_i32 v[110:111], s[14:15], v113, s85, v[110:111]
	v_ashrrev_i32_e32 v113, 31, v112
	v_lshl_add_u64 v[110:111], v[110:111], 0, s[26:27]
	v_lshlrev_b64 v[112:113], 9, v[112:113]
	v_lshl_add_u64 v[116:117], v[110:111], 0, v[168:169]
	v_lshl_add_u64 v[114:115], v[32:33], 0, v[112:113]
	s_mov_b64 s[14:15], 0x1000
	global_load_dwordx4 v[120:123], v[114:115], off
	global_load_dwordx4 v[124:127], v[114:115], off offset:16
	global_load_dwordx4 v[128:131], v[114:115], off offset:48
	global_load_dwordx4 v[132:135], v[114:115], off offset:32
	v_lshl_add_u64 v[118:119], v[116:117], 0, s[14:15]
	global_load_dwordx4 v[136:139], v[118:119], off
	global_load_dwordx4 v[140:143], v[118:119], off offset:128
	global_load_dwordx4 v[144:147], v[118:119], off offset:1024
	global_load_dwordx4 v[148:151], v[118:119], off offset:1152
	s_waitcnt vmcnt(0)
.LBB0_464:
	s_and_b32 s5, s4, 3
	s_getpc_b64 s[10:11]
	s_add_u32 s10, s10, _ZN2mk5LOG2GE@rel32@lo+4
	s_addc_u32 s11, s11, _ZN2mk5LOG2GE@rel32@hi+12
	s_movk_i32 s15, 0xf000
	s_lshl_b32 s5, s5, 2
	v_add_co_u32_e32 v36, vcc, s15, v34
	s_load_dword s5, s[10:11], s5 offset:0x0
	v_addc_co_u32_e32 v37, vcc, -1, v35, vcc
	s_waitcnt vmcnt(16)
	v_mov_b32_e32 v0, v120
	v_mov_b32_e32 v1, v121
	v_mov_b32_e32 v2, v122
	v_mov_b32_e32 v3, v123
	v_mov_b32_e32 v4, v124
	v_mov_b32_e32 v5, v125
	v_mov_b32_e32 v6, v126
	v_mov_b32_e32 v7, v127
	v_mov_b32_e32 v8, v128
	v_mov_b32_e32 v9, v129
	v_mov_b32_e32 v10, v130
	v_mov_b32_e32 v11, v131
	v_mov_b32_e32 v12, v132
	v_mov_b32_e32 v13, v133
	v_mov_b32_e32 v14, v134
	v_mov_b32_e32 v15, v135
	v_mov_b32_e32 v16, v136
	v_mov_b32_e32 v17, v137
	v_mov_b32_e32 v18, v138
	v_mov_b32_e32 v19, v139
	v_mov_b32_e32 v20, v140
	v_mov_b32_e32 v21, v141
	v_mov_b32_e32 v22, v142
	v_mov_b32_e32 v23, v143
	v_mov_b32_e32 v24, v144
	v_mov_b32_e32 v25, v145
	v_mov_b32_e32 v26, v146
	v_mov_b32_e32 v27, v147
	v_mov_b32_e32 v28, v148
	v_mov_b32_e32 v29, v149
	v_mov_b32_e32 v30, v150
	v_mov_b32_e32 v31, v151
	s_add_i32 s4, s4, s24
	s_add_i32 s12, s12, s76
	s_cmpk_lt_i32 s4, 0x400
	s_cselect_b32 s16, 1, 0
	s_cbranch_scc0 .Levena_nopf
	s_and_b32 s13, s12, 0xfc0
	s_and_b32 s14, s12, 0xffffffc0
	s_and_b32 s26, s4, 3
	s_lshl_b32 s26, s26, 8
	v_mov_b64_e32 v[110:111], s[6:7]
	v_add_u32_e32 v113, s14, v38
	v_add_u32_e32 v112, s13, v38
	v_mad_i64_i32 v[110:111], s[14:15], v113, s85, v[110:111]
	v_ashrrev_i32_e32 v113, 31, v112
	v_lshl_add_u64 v[110:111], v[110:111], 0, s[26:27]
	v_lshlrev_b64 v[112:113], 9, v[112:113]
	v_lshl_add_u64 v[116:117], v[110:111], 0, v[168:169]
	v_lshl_add_u64 v[114:115], v[32:33], 0, v[112:113]
	s_mov_b64 s[14:15], 0x1000
	global_load_dwordx4 v[120:123], v[114:115], off
	global_load_dwordx4 v[124:127], v[114:115], off offset:16
	global_load_dwordx4 v[128:131], v[114:115], off offset:48
	global_load_dwordx4 v[132:135], v[114:115], off offset:32
	v_lshl_add_u64 v[118:119], v[116:117], 0, s[14:15]
	global_load_dwordx4 v[136:139], v[118:119], off
	global_load_dwordx4 v[140:143], v[118:119], off offset:128
	global_load_dwordx4 v[144:147], v[118:119], off offset:1024
	global_load_dwordx4 v[148:151], v[118:119], off offset:1152
.Levena_nopf:
	s_waitcnt lgkmcnt(0)
	v_mul_f32_e32 v44, s5, v39
	v_exp_f32_e32 v44, v44
	s_nop 0
	v_mul_f32_e32 v44, 0x3db504f3, v44
	ds_write_b128 v40, v[24:27] offset:17408
	ds_write_b128 v40, v[28:31] offset:17536
	v_mov_b32_e32 v46, v0
	v_mov_b32_e32 v47, v2
	v_mov_b32_e32 v2, v1
	v_mov_b32_e32 v0, v4
	v_mov_b32_e32 v1, v6
	v_mov_b32_e32 v6, v5
	v_mov_b32_e32 v4, v12
	v_mov_b32_e32 v5, v14
	v_mov_b32_e32 v14, v13
	v_mov_b32_e32 v13, v10
	v_mov_b32_e32 v10, v9
	v_lshlrev_b32_e32 v48, 16, v20
	v_and_b32_e32 v49, 0xffff0000, v20
	v_lshlrev_b32_e32 v20, 16, v21
	v_and_b32_e32 v21, 0xffff0000, v21
	v_lshlrev_b32_e32 v52, 16, v22
	v_and_b32_e32 v53, 0xffff0000, v22
	v_lshlrev_b32_e32 v22, 16, v23
	v_and_b32_e32 v23, 0xffff0000, v23
	v_mov_b32_e32 v12, v8
	v_lshlrev_b32_e32 v8, 16, v16
	v_and_b32_e32 v9, 0xffff0000, v16
	v_lshlrev_b32_e32 v16, 16, v17
	v_and_b32_e32 v17, 0xffff0000, v17
	v_lshlrev_b32_e32 v50, 16, v18
	v_and_b32_e32 v51, 0xffff0000, v18
	v_lshlrev_b32_e32 v18, 16, v19
	v_and_b32_e32 v19, 0xffff0000, v19
	v_pk_mul_f32 v[24:25], v[2:3], v[48:49]
	v_pk_mul_f32 v[26:27], v[46:47], v[48:49]
	v_pk_mul_f32 v[28:29], v[6:7], v[20:21]
	v_pk_mul_f32 v[30:31], v[14:15], v[52:53]
	v_pk_mul_f32 v[48:49], v[4:5], v[52:53]
	v_pk_mul_f32 v[52:53], v[10:11], v[22:23]
	v_pk_mul_f32 v[20:21], v[0:1], v[20:21]
	v_pk_mul_f32 v[22:23], v[12:13], v[22:23]
	v_pk_fma_f32 v[24:25], v[46:47], v[8:9], v[24:25] neg_lo:[0,0,1] neg_hi:[0,0,1]
	v_pk_fma_f32 v[2:3], v[2:3], v[8:9], v[26:27]
	v_pk_fma_f32 v[0:1], v[0:1], v[16:17], v[28:29] neg_lo:[0,0,1] neg_hi:[0,0,1]
	v_pk_fma_f32 v[4:5], v[4:5], v[50:51], v[30:31] neg_lo:[0,0,1] neg_hi:[0,0,1]
	v_pk_fma_f32 v[12:13], v[12:13], v[18:19], v[52:53] neg_lo:[0,0,1] neg_hi:[0,0,1]
	v_pk_fma_f32 v[6:7], v[6:7], v[16:17], v[20:21]
	v_pk_fma_f32 v[8:9], v[14:15], v[50:51], v[48:49]
	v_pk_fma_f32 v[10:11], v[10:11], v[18:19], v[22:23]
	v_pk_mul_f32 v[14:15], v[44:45], v[24:25] op_sel_hi:[0,1]
	v_pk_mul_f32 v[2:3], v[44:45], v[2:3] op_sel_hi:[0,1]
	v_pk_mul_f32 v[16:17], v[44:45], v[0:1] op_sel_hi:[0,1]
	v_pk_mul_f32 v[18:19], v[44:45], v[4:5] op_sel_hi:[0,1]
	v_pk_mul_f32 v[12:13], v[44:45], v[12:13] op_sel_hi:[0,1]
	v_pk_mul_f32 v[6:7], v[44:45], v[6:7] op_sel_hi:[0,1]
	v_pk_mul_f32 v[8:9], v[44:45], v[8:9] op_sel_hi:[0,1]
	v_pk_mul_f32 v[10:11], v[44:45], v[10:11] op_sel_hi:[0,1]
	v_cvt_pk_bf16_f32 v0, v14, v15
	v_cvt_pk_bf16_f32 v4, v2, v3
	v_cvt_pk_bf16_f32 v1, v16, v17
	v_cvt_pk_bf16_f32 v2, v18, v19
	v_cvt_pk_bf16_f32 v3, v12, v13
	v_cvt_pk_bf16_f32 v5, v6, v7
	v_cvt_pk_bf16_f32 v6, v8, v9
	v_cvt_pk_bf16_f32 v7, v10, v11
	ds_write_b128 v40, v[0:3]
	ds_write_b128 v40, v[4:7] offset:128
	s_waitcnt lgkmcnt(0)
	s_barrier
	ds_read_u16 v0, v41 offset:17408
	ds_read_u16 v1, v41 offset:17680
	ds_read_u16 v2, v41 offset:17952
	ds_read_u16 v3, v41 offset:18224
	ds_read_u16 v4, v41 offset:18496
	ds_read_u16 v5, v41 offset:18768
	ds_read_u16 v6, v41 offset:19040
	ds_read_u16 v7, v41 offset:19312
	ds_read_u16 v8, v42
	ds_read_u16 v9, v42 offset:272
	ds_read_u16 v10, v42 offset:544
	ds_read_u16 v11, v42 offset:816
	ds_read_u16 v12, v42 offset:1088
	ds_read_u16 v13, v42 offset:1360
	ds_read_u16 v14, v42 offset:1632
	ds_read_u16 v15, v42 offset:1904
	ds_read_u16 v20, v43
	ds_read_u16 v21, v43 offset:272
	ds_read_u16 v22, v43 offset:544
	ds_read_u16 v23, v43 offset:816
	ds_read_u16 v24, v43 offset:1088
	ds_read_u16 v25, v43 offset:1360
	ds_read_u16 v26, v43 offset:1632
	ds_read_u16 v27, v43 offset:1904
	ds_read_u16 v28, v41 offset:21760
	ds_read_u16 v29, v41 offset:22032
	ds_read_u16 v45, v41 offset:22304
	ds_read_u16 v46, v41 offset:22576
	ds_read_u16 v47, v41 offset:22848
	ds_read_u16 v48, v41 offset:23120
	ds_read_u16 v49, v41 offset:23392
	ds_read_u16 v50, v41 offset:23664
	ds_read_u16 v51, v42 offset:4352
	ds_read_u16 v52, v42 offset:4624
	ds_read_u16 v53, v42 offset:4896
	ds_read_u16 v54, v42 offset:5168
	ds_read_u16 v55, v42 offset:5440
	ds_read_u16 v56, v42 offset:5712
	ds_read_u16 v57, v42 offset:5984
	ds_read_u16 v58, v42 offset:6256
	ds_read_u16 v59, v43 offset:4352
	ds_read_u16 v60, v43 offset:4624
	ds_read_u16 v61, v43 offset:4896
	ds_read_u16 v62, v43 offset:5168
	ds_read_u16 v63, v43 offset:5440
	ds_read_u16 v64, v43 offset:5712
	ds_read_u16 v65, v43 offset:5984
	ds_read_u16 v66, v43 offset:6256
	ds_read_u16 v67, v41 offset:26112
	ds_read_u16 v68, v41 offset:26384
	ds_read_u16 v69, v41 offset:26656
	ds_read_u16 v70, v41 offset:26928
	ds_read_u16 v71, v41 offset:27200
	ds_read_u16 v72, v41 offset:27472
	ds_read_u16 v73, v41 offset:27744
	ds_read_u16 v74, v41 offset:28016
	ds_read_u16 v75, v42 offset:8704
	ds_read_u16 v76, v42 offset:8976
	ds_read_u16 v77, v42 offset:9248
	ds_read_u16 v78, v42 offset:9520
	ds_read_u16 v79, v42 offset:9792
	ds_read_u16 v80, v42 offset:10064
	ds_read_u16 v81, v42 offset:10336
	ds_read_u16 v82, v42 offset:10608
	ds_read_u16 v83, v43 offset:8704
	ds_read_u16 v84, v43 offset:8976
	ds_read_u16 v85, v43 offset:9248
	ds_read_u16 v86, v43 offset:9520
	ds_read_u16 v87, v43 offset:9792
	ds_read_u16 v88, v43 offset:10064
	ds_read_u16 v89, v43 offset:10336
	ds_read_u16 v90, v43 offset:10608
	ds_read_u16 v91, v41 offset:30464
	ds_read_u16 v92, v41 offset:30736
	ds_read_u16 v93, v41 offset:31008
	ds_read_u16 v94, v41 offset:31280
	ds_read_u16 v95, v41 offset:31552
	ds_read_u16 v96, v41 offset:31824
	ds_read_u16 v97, v41 offset:32096
	ds_read_u16 v98, v41 offset:32368
	ds_read_u16 v99, v42 offset:13056
	ds_read_u16 v100, v42 offset:13328
	ds_read_u16 v101, v42 offset:13600
	ds_read_u16 v102, v42 offset:13872
	ds_read_u16 v103, v42 offset:14144
	ds_read_u16 v104, v42 offset:14416
	ds_read_u16 v105, v42 offset:14688
	ds_read_u16 v106, v42 offset:14960
	s_waitcnt lgkmcnt(14)
	v_lshl_or_b32 v16, v1, 16, v0
	v_lshl_or_b32 v17, v3, 16, v2
	v_lshl_or_b32 v18, v5, 16, v4
	v_lshl_or_b32 v19, v7, 16, v6
	v_lshl_or_b32 v0, v9, 16, v8
	v_lshl_or_b32 v1, v11, 16, v10
	v_lshl_or_b32 v2, v13, 16, v12
	v_lshl_or_b32 v3, v15, 16, v14
	v_lshl_or_b32 v44, v29, 16, v28
	v_lshl_or_b32 v45, v46, 16, v45
	v_mfma_f32_32x32x16_bf16 v[0:15], v[16:19], v[0:3], 0
	v_lshl_or_b32 v46, v48, 16, v47
	v_lshl_or_b32 v47, v50, 16, v49
	v_lshl_or_b32 v20, v21, 16, v20
	v_lshl_or_b32 v21, v23, 16, v22
	v_lshl_or_b32 v22, v25, 16, v24
	v_lshl_or_b32 v23, v27, 16, v26
	v_lshl_or_b32 v48, v52, 16, v51
	v_lshl_or_b32 v49, v54, 16, v53
	v_mfma_f32_32x32x16_bf16 v[16:31], v[16:19], v[20:23], 0
	v_lshl_or_b32 v50, v56, 16, v55
	v_lshl_or_b32 v51, v58, 16, v57
	v_lshl_or_b32 v52, v68, 16, v67
	v_lshl_or_b32 v53, v70, 16, v69
	v_lshl_or_b32 v54, v72, 16, v71
	v_lshl_or_b32 v55, v74, 16, v73
	ds_read_u16 v107, v43 offset:13056
	ds_read_u16 v108, v43 offset:13328
	v_mfma_f32_32x32x16_bf16 v[0:15], v[44:47], v[48:51], v[0:15]
	v_lshl_or_b32 v48, v60, 16, v59
	v_lshl_or_b32 v49, v62, 16, v61
	v_lshl_or_b32 v50, v64, 16, v63
	v_lshl_or_b32 v51, v66, 16, v65
	ds_read_u16 v56, v43 offset:13600
	ds_read_u16 v57, v43 offset:13872
	ds_read_u16 v58, v43 offset:14144
	ds_read_u16 v59, v43 offset:14416
	v_mfma_f32_32x32x16_bf16 v[16:31], v[44:47], v[48:51], v[16:31]
	v_lshl_or_b32 v44, v76, 16, v75
	v_lshl_or_b32 v45, v78, 16, v77
	v_lshl_or_b32 v46, v80, 16, v79
	v_lshl_or_b32 v47, v82, 16, v81
	v_lshl_or_b32 v48, v92, 16, v91
	s_waitcnt lgkmcnt(14)
	v_lshl_or_b32 v49, v94, 16, v93
	v_lshl_or_b32 v50, v96, 16, v95
	v_mfma_f32_32x32x16_bf16 v[0:15], v[52:55], v[44:47], v[0:15]
	v_lshl_or_b32 v51, v98, 16, v97
	v_lshl_or_b32 v44, v84, 16, v83
	v_lshl_or_b32 v45, v86, 16, v85
	v_lshl_or_b32 v46, v88, 16, v87
	v_lshl_or_b32 v47, v90, 16, v89
	s_nop 1
	v_mfma_f32_32x32x16_bf16 v[16:31], v[52:55], v[44:47], v[16:31]
	s_waitcnt lgkmcnt(12)
	v_lshl_or_b32 v44, v100, 16, v99
	s_waitcnt lgkmcnt(10)
	v_lshl_or_b32 v45, v102, 16, v101
	s_waitcnt lgkmcnt(8)
	v_lshl_or_b32 v46, v104, 16, v103
	s_waitcnt lgkmcnt(6)
	v_lshl_or_b32 v47, v106, 16, v105
	s_nop 1
	v_mfma_f32_32x32x16_bf16 v[0:15], v[48:51], v[44:47], v[0:15]
	ds_read_u16 v47, v43 offset:14688
	ds_read_u16 v52, v43 offset:14960
	s_waitcnt lgkmcnt(6)
	v_lshl_or_b32 v44, v108, 16, v107
	s_waitcnt lgkmcnt(4)
	v_lshl_or_b32 v45, v57, 16, v56
	s_waitcnt lgkmcnt(2)
	v_lshl_or_b32 v46, v59, 16, v58
	s_waitcnt lgkmcnt(0)
	v_lshl_or_b32 v47, v52, 16, v47
	s_nop 1
	v_cvt_pk_bf16_f32 v0, v0, v1
	v_mfma_f32_32x32x16_bf16 v[16:31], v[48:51], v[44:47], v[16:31]
	v_cvt_pk_bf16_f32 v2, v2, v3
	v_cvt_pk_bf16_f32 v4, v4, v5
	v_cvt_pk_bf16_f32 v6, v6, v7
	v_cvt_pk_bf16_f32 v8, v8, v9
	v_cvt_pk_bf16_f32 v10, v10, v11
	v_cvt_pk_bf16_f32 v12, v12, v13
	v_cvt_pk_bf16_f32 v14, v14, v15
	s_nop 4
	v_cvt_pk_bf16_f32 v16, v16, v17
	v_cvt_pk_bf16_f32 v18, v18, v19
	v_cvt_pk_bf16_f32 v20, v20, v21
	v_cvt_pk_bf16_f32 v22, v22, v23
	v_cvt_pk_bf16_f32 v24, v24, v25
	v_cvt_pk_bf16_f32 v26, v26, v27
	v_cvt_pk_bf16_f32 v28, v28, v29
	v_cvt_pk_bf16_f32 v30, v30, v31
	v_mov_b32_dpp v1, v0 quad_perm:[1,0,3,2] row_mask:0xf bank_mask:0xf
	v_mov_b32_dpp v3, v2 quad_perm:[1,0,3,2] row_mask:0xf bank_mask:0xf
	v_mov_b32_dpp v5, v4 quad_perm:[1,0,3,2] row_mask:0xf bank_mask:0xf
	v_mov_b32_dpp v7, v6 quad_perm:[1,0,3,2] row_mask:0xf bank_mask:0xf
	v_mov_b32_dpp v9, v8 quad_perm:[1,0,3,2] row_mask:0xf bank_mask:0xf
	v_mov_b32_dpp v11, v10 quad_perm:[1,0,3,2] row_mask:0xf bank_mask:0xf
	v_mov_b32_dpp v13, v12 quad_perm:[1,0,3,2] row_mask:0xf bank_mask:0xf
	v_mov_b32_dpp v15, v14 quad_perm:[1,0,3,2] row_mask:0xf bank_mask:0xf
	v_mov_b32_dpp v17, v16 quad_perm:[1,0,3,2] row_mask:0xf bank_mask:0xf
	v_mov_b32_dpp v19, v18 quad_perm:[1,0,3,2] row_mask:0xf bank_mask:0xf
	v_mov_b32_dpp v21, v20 quad_perm:[1,0,3,2] row_mask:0xf bank_mask:0xf
	v_mov_b32_dpp v23, v22 quad_perm:[1,0,3,2] row_mask:0xf bank_mask:0xf
	v_mov_b32_dpp v25, v24 quad_perm:[1,0,3,2] row_mask:0xf bank_mask:0xf
	v_mov_b32_dpp v27, v26 quad_perm:[1,0,3,2] row_mask:0xf bank_mask:0xf
	v_mov_b32_dpp v29, v28 quad_perm:[1,0,3,2] row_mask:0xf bank_mask:0xf
	v_mov_b32_dpp v31, v30 quad_perm:[1,0,3,2] row_mask:0xf bank_mask:0xf
	v_perm_b32 v0, v1, v0, v162
	v_perm_b32 v2, v3, v2, v162
	v_perm_b32 v4, v5, v4, v162
	v_perm_b32 v6, v7, v6, v162
	v_perm_b32 v8, v9, v8, v162
	v_perm_b32 v10, v11, v10, v162
	v_perm_b32 v12, v13, v12, v162
	v_perm_b32 v14, v15, v14, v162
	v_perm_b32 v16, v17, v16, v162
	v_perm_b32 v18, v19, v18, v162
	v_perm_b32 v20, v21, v20, v162
	v_perm_b32 v22, v23, v22, v162
	v_perm_b32 v24, v25, v24, v162
	v_perm_b32 v26, v27, v26, v162
	v_perm_b32 v28, v29, v28, v162
	v_perm_b32 v30, v31, v30, v162
	v_lshl_add_u64 v[158:159], v[36:37], 0, v[156:157]
	v_lshl_add_u64 v[160:161], v[34:35], 0, v[156:157]
	global_store_dword v[158:159], v0, off offset:-2880
	global_store_dword v[158:159], v16, off offset:-2816
	global_store_dword v[158:159], v2, off offset:-2368
	global_store_dword v[158:159], v18, off offset:-2304
	global_store_dword v[158:159], v4, off offset:-832
	global_store_dword v[158:159], v20, off offset:-768
	global_store_dword v[158:159], v6, off offset:-320
	global_store_dword v[158:159], v22, off offset:-256
	global_store_dword v[160:161], v8, off offset:-2880
	global_store_dword v[160:161], v24, off offset:-2816
	global_store_dword v[160:161], v10, off offset:-2368
	global_store_dword v[160:161], v26, off offset:-2304
	global_store_dword v[160:161], v12, off offset:-832
	global_store_dword v[160:161], v28, off offset:-768
	global_store_dword v[160:161], v14, off offset:-320
	global_store_dword v[160:161], v30, off offset:-256
	s_waitcnt lgkmcnt(0)
	s_barrier
	v_lshl_add_u64 v[34:35], v[34:35], 0, s[34:35]
	s_cmp_lg_u32 s16, 0
	s_cbranch_scc1 .LBB0_464
